# P1 128x128 tiles: K-loop re-emitted with the next K-tile's 8 LDS-DMA loads spread between the MFMA pairs of kh=0 (same wait+barrier per K-tile)
# speedup vs baseline: 1.0165x; 1.0165x over previous
; #define GLDS_STAGE(st, kt_) do { \
;         _Pragma("unroll") for (int i_ = 0; i_ < FI; ++i_) { \
;             glds16(ap + (size_t)(32 * i_) * lda + (kt_) * 64, l3a + (st) + tid * 16 + i_ * 4096); \
;             glds16(bp + (size_t)(32 * i_) * ldb + (kt_) * 64, l3a + (st) + OPB + tid * 16 + i_ * 4096); } } while (0)
; #define GLDS_STAGE(st, kt_) do { \
;         _Pragma("unroll") for (int i_ = 0; i_ < 4; ++i_) { \
;             glds16(ap + (size_t)(64 * i_) * lda + (kt_) * 64, l3a + (st) + tid * 16 + i_ * 8192); \
;             glds16(bp + (size_t)(64 * i_) * ldb + (kt_) * 64, l3a + (st) + 32768 + tid * 16 + i_ * 8192); } } while (0)
; template <int WT, class Epi>
; DEV void gemm_tile(const bf16_t* __restrict__ A, int lda, const bf16_t* __restrict__ Bt, int ldb, int K, unsigned char* lds, const Epi& epi) {
;     ...
;     constexpr int NSTG = 65536 / STB;
; #pragma unroll
;     for (int s_ = 0; s_ < NSTG - 1; ++s_) if (s_ < nk) GLDS_STAGE(s_ * STB, s_);
;     const int aoff = (wr * WT + fr) * 128, boff = OPB + (wc * WT + fr) * 128, sw = fr & 7;
;     int cur = 0, nxt = (NSTG - 1) * STB;
;     for (int kt = 0; kt < nk; ++kt) {
;         if (NSTG == 4 && kt + 2 < nk) { if (FI == 2) asm volatile("s_waitcnt vmcnt(8)" ::: "memory"); else asm volatile("s_waitcnt vmcnt(0)" ::: "memory"); }
;         else asm volatile("s_waitcnt vmcnt(0)" ::: "memory");
;         __syncthreads();
;         if (kt + NSTG - 1 < nk) GLDS_STAGE(nxt, kt + NSTG - 1);
; #pragma unroll
;         for (int kh = 0; kh < 2; ++kh) {
;             bf16x8 af[FI], bfr[FI];
;             const int ch = ((kh * 4 + fq) ^ sw) << 4;
; #pragma unroll
;             for (int i = 0; i < FI; ++i) { af[i] = *(const bf16x8*)(lds + cur + aoff + i * 2048 + ch); bfr[i] = *(const bf16x8*)(lds + cur + boff + i * 2048 + ch); }
; #pragma unroll
;             for (int mi = 0; mi < FI; ++mi)
; #pragma unroll
;                 for (int ni = 0; ni < FI; ++ni) acc[mi][ni] = __builtin_amdgcn_mfma_f32_16x16x32_bf16(bfr[ni], af[mi], acc[mi][ni], 0, 0, 0);
;         }
;         nxt = cur; cur += STB; if (cur == NSTG * STB) cur = 0;
;     }
.Lg128s_0_loop:
	s_add_i32 s40, s53, s42
	s_xor_b32 s43, s42, 0x8000
	v_add_u32_e32 v122, s40, v82
	v_add_u32_e32 v123, s40, v85
	v_add_u32_e32 v143, v122, v81
	v_add_u32_e32 v144, v123, v81
	v_add_u32_e32 v122, v122, v84
	v_add_u32_e32 v123, v123, v84
	s_waitcnt vmcnt(0)
	s_barrier
	v_add_u32_e32 v142, s43, v83
	v_lshl_add_u64 v[124:125], v[78:79], 0, s[4:5]
	v_lshl_add_u64 v[126:127], v[76:77], 0, s[4:5]
	v_readfirstlane_b32 s38, v142
	s_add_i32 s39, s38, 0x4000
	ds_read_b128 v[90:93], v123 offset:16384
	ds_read_b128 v[94:97], v123 offset:18432
	ds_read_b128 v[106:109], v122
	ds_read_b128 v[110:113], v122 offset:2048
	ds_read_b128 v[98:101], v123 offset:20480
	ds_read_b128 v[102:105], v123 offset:22528
	ds_read_b128 v[114:117], v122 offset:4096
	ds_read_b128 v[118:121], v122 offset:6144
	s_waitcnt lgkmcnt(5)
	v_mfma_f32_16x16x32_bf16 v[62:65], v[90:93], v[106:109], v[62:65]
	v_mfma_f32_16x16x32_bf16 v[54:57], v[94:97], v[106:109], v[54:57]
	s_mov_b32 m0, s38
	s_nop 0
	global_load_lds_dwordx4 v[124:125], off
	s_waitcnt lgkmcnt(4)
	v_mfma_f32_16x16x32_bf16 v[38:41], v[90:93], v[110:113], v[38:41]
	v_mfma_f32_16x16x32_bf16 v[34:37], v[94:97], v[110:113], v[34:37]
	s_mov_b32 m0, s39
	s_nop 0
	global_load_lds_dwordx4 v[126:127], off
	s_waitcnt lgkmcnt(2)
	v_mfma_f32_16x16x32_bf16 v[50:53], v[98:101], v[106:109], v[50:53]
	v_mfma_f32_16x16x32_bf16 v[46:49], v[102:105], v[106:109], v[46:49]
	s_add_i32 s40, s38, 0x1000
	s_mov_b32 m0, s40
	v_lshl_add_u64 v[128:129], v[124:125], 0, s[30:31]
	global_load_lds_dwordx4 v[128:129], off
	v_mfma_f32_16x16x32_bf16 v[30:33], v[98:101], v[110:113], v[30:33]
	v_mfma_f32_16x16x32_bf16 v[26:29], v[102:105], v[110:113], v[26:29]
	s_add_i32 s40, s39, 0x1000
	s_mov_b32 m0, s40
	v_lshl_add_u64 v[140:141], v[126:127], 0, s[30:31]
	global_load_lds_dwordx4 v[140:141], off
	s_waitcnt lgkmcnt(1)
	v_mfma_f32_16x16x32_bf16 v[22:25], v[90:93], v[114:117], v[22:25]
	v_mfma_f32_16x16x32_bf16 v[18:21], v[94:97], v[114:117], v[18:21]
	s_add_i32 s40, s38, 0x2000
	s_mov_b32 m0, s40
	v_lshl_add_u64 v[128:129], v[124:125], 0, s[34:35]
	global_load_lds_dwordx4 v[128:129], off
	v_mfma_f32_16x16x32_bf16 v[14:17], v[98:101], v[114:117], v[14:17]
	v_mfma_f32_16x16x32_bf16 v[10:13], v[102:105], v[114:117], v[10:13]
	s_add_i32 s40, s39, 0x2000
	s_mov_b32 m0, s40
	v_lshl_add_u64 v[140:141], v[126:127], 0, s[34:35]
	global_load_lds_dwordx4 v[140:141], off
	s_waitcnt lgkmcnt(0)
	v_mfma_f32_16x16x32_bf16 v[6:9], v[90:93], v[118:121], v[6:9]
	v_mfma_f32_16x16x32_bf16 v[2:5], v[94:97], v[118:121], v[2:5]
	s_add_i32 s40, s38, 0x3000
	s_mov_b32 m0, s40
	v_lshl_add_u64 v[128:129], v[124:125], 0, s[36:37]
	global_load_lds_dwordx4 v[128:129], off
	v_mfma_f32_16x16x32_bf16 v[58:61], v[98:101], v[118:121], v[58:61]
	v_mfma_f32_16x16x32_bf16 v[42:45], v[102:105], v[118:121], v[42:45]
	s_add_i32 s40, s39, 0x3000
	s_mov_b32 m0, s40
	v_lshl_add_u64 v[140:141], v[126:127], 0, s[36:37]
	global_load_lds_dwordx4 v[140:141], off
	v_mov_b32_e32 v122, v143
	v_mov_b32_e32 v123, v144
	ds_read_b128 v[90:93], v123 offset:16384
	ds_read_b128 v[94:97], v123 offset:18432
	ds_read_b128 v[106:109], v122
	ds_read_b128 v[110:113], v122 offset:2048
	ds_read_b128 v[98:101], v123 offset:20480
	ds_read_b128 v[102:105], v123 offset:22528
	ds_read_b128 v[114:117], v122 offset:4096
	ds_read_b128 v[118:121], v122 offset:6144
	s_waitcnt lgkmcnt(5)
	v_mfma_f32_16x16x32_bf16 v[62:65], v[90:93], v[106:109], v[62:65]
	v_mfma_f32_16x16x32_bf16 v[54:57], v[94:97], v[106:109], v[54:57]
	s_waitcnt lgkmcnt(4)
	v_mfma_f32_16x16x32_bf16 v[38:41], v[90:93], v[110:113], v[38:41]
	v_mfma_f32_16x16x32_bf16 v[34:37], v[94:97], v[110:113], v[34:37]
	s_waitcnt lgkmcnt(2)
	v_mfma_f32_16x16x32_bf16 v[50:53], v[98:101], v[106:109], v[50:53]
	v_mfma_f32_16x16x32_bf16 v[46:49], v[102:105], v[106:109], v[46:49]
	v_mfma_f32_16x16x32_bf16 v[30:33], v[98:101], v[110:113], v[30:33]
	v_mfma_f32_16x16x32_bf16 v[26:29], v[102:105], v[110:113], v[26:29]
	s_waitcnt lgkmcnt(1)
	v_mfma_f32_16x16x32_bf16 v[22:25], v[90:93], v[114:117], v[22:25]
	v_mfma_f32_16x16x32_bf16 v[18:21], v[94:97], v[114:117], v[18:21]
	v_mfma_f32_16x16x32_bf16 v[14:17], v[98:101], v[114:117], v[14:17]
	v_mfma_f32_16x16x32_bf16 v[10:13], v[102:105], v[114:117], v[10:13]
	s_waitcnt lgkmcnt(0)
	v_mfma_f32_16x16x32_bf16 v[6:9], v[90:93], v[118:121], v[6:9]
	v_mfma_f32_16x16x32_bf16 v[2:5], v[94:97], v[118:121], v[2:5]
	v_mfma_f32_16x16x32_bf16 v[58:61], v[98:101], v[118:121], v[58:61]
	v_mfma_f32_16x16x32_bf16 v[42:45], v[102:105], v[118:121], v[42:45]
	s_add_u32 s4, s4, 0x80
	s_addc_u32 s5, s5, 0
	s_xor_b32 s42, s42, 0x8000
	s_cmp_lg_u32 s4, 0xf80
	s_cbranch_scc1 .Lg128s_0_loop
; template <int WT, class Epi>
; DEV void gemm_tile(const bf16_t* __restrict__ A, int lda, const bf16_t* __restrict__ Bt, int ldb, int K, unsigned char* lds, const Epi& epi) {
;     ...
;         for (int kh = 0; kh < 2; ++kh) {
;             bf16x8 af[FI], bfr[FI];
;             const int ch = ((kh * 4 + fq) ^ sw) << 4;
; #pragma unroll
;             for (int i = 0; i < FI; ++i) { af[i] = *(const bf16x8*)(lds + cur + aoff + i * 2048 + ch); bfr[i] = *(const bf16x8*)(lds + cur + boff + i * 2048 + ch); }
; #pragma unroll
;             for (int mi = 0; mi < FI; ++mi)
; #pragma unroll
;                 for (int ni = 0; ni < FI; ++ni) acc[mi][ni] = __builtin_amdgcn_mfma_f32_16x16x32_bf16(bfr[ni], af[mi], acc[mi][ni], 0, 0, 0);
;         }
;         nxt = cur; cur += STB; if (cur == NSTG * STB) cur = 0;
;     }
;     ...
;     __syncthreads();
;     if constexpr (Epi::STAGE) {
;         constexpr int RB = 4 * WT, CPR = RB / 16;
; #pragma unroll
;         for (int mi = 0; mi < FI; ++mi)
; #pragma unroll
;             for (int ni = 0; ni < FI; ++ni) {
;                 const int row = wr * WT + mi * 16 + fr, col = wc * WT + ni * 16 + fq * 4;
;                 const f32x4 v = epi.xform(row, col, acc[mi][ni]);
;                 uint2 w; w.x = cvt_pk_bf16(v[0], v[1]); w.y = cvt_pk_bf16(v[2], v[3]);
;                 *(uint2*)(lds + row * RB + ((((col >> 3) ^ (row & (CPR - 1))) << 4) | (((col >> 2) & 1) << 3))) = w;
;             }
;         __syncthreads();
; #pragma unroll
;         for (int i = 0; i < (2 * WT * CPR) / 256; ++i) {
;             const int idx = tid + 256 * i, row = idx / CPR, cp = idx % CPR, c = cp ^ (row & (CPR - 1));
;             const uint4 d = *(const uint4*)(lds + row * RB + (cp << 4));
;             *(uint4*)(epi.obase + (size_t)row * epi.old + c * 8) = epi.finish(row, c * 8, d);
;         }
;         __syncthreads();
;     } else {
; #pragma unroll
;         for (int mi = 0; mi < FI; ++mi)
; #pragma unroll
;             for (int ni = 0; ni < FI; ++ni) epi(wr * WT + mi * 16 + fr, wc * WT + ni * 16 + fq * 4, acc[mi][ni]);
;     DEV void operator()(int r, int c, f32x4 v) const {
;         const int row = m0 + r, col = n0 + c;
;         if (col < D) {
;             __builtin_nontemporal_store(v, (f32x4*)(out + O_MK + (size_t)row * D + col));
;             store_bf4(mkb + (size_t)row * LDB + col, v);
;         } else {
	s_mov_b32 m0, s46
	v_add_u32_e32 v102, s53, v85
	v_add_u32_e32 v103, s53, v82
	v_add_u32_e32 v98, v102, v84
	v_add_u32_e32 v104, v103, v84
	s_waitcnt vmcnt(0)
	s_barrier
	ds_read_b128 v[76:79], v98 offset:49152
	ds_read_b128 v[90:93], v98 offset:51200
	ds_read_b128 v[82:85], v104 offset:32768
	ds_read_b128 v[94:97], v98 offset:53248
	ds_read_b128 v[98:101], v98 offset:55296
	s_waitcnt lgkmcnt(2)
	v_mfma_f32_16x16x32_bf16 v[62:65], v[76:79], v[82:85], v[62:65]
	v_add_u32_e32 v102, v102, v81
	v_add_u32_e32 v81, v103, v81
	s_lshl_b32 s11, s8, 7
	v_mfma_f32_16x16x32_bf16 v[54:57], v[90:93], v[82:85], v[54:57]
	s_lshl_b32 s4, s7, 7
	s_cmpk_gt_u32 s6, 0x7f
	s_cselect_b64 s[6:7], -1, 0
	s_waitcnt lgkmcnt(1)
	v_mfma_f32_16x16x32_bf16 v[50:53], v[94:97], v[82:85], v[50:53]
	ds_read_b128 v[106:109], v81 offset:34816
	s_and_b64 vcc, exec, s[6:7]
	ds_read_b128 v[110:113], v81 offset:38912
	s_waitcnt lgkmcnt(2)
	v_mfma_f32_16x16x32_bf16 v[46:49], v[98:101], v[82:85], v[46:49]
	ds_read_b128 v[82:85], v104 offset:34816
	s_waitcnt lgkmcnt(0)
	v_mfma_f32_16x16x32_bf16 v[38:41], v[76:79], v[82:85], v[38:41]
	v_mfma_f32_16x16x32_bf16 v[34:37], v[90:93], v[82:85], v[34:37]
	v_mfma_f32_16x16x32_bf16 v[30:33], v[94:97], v[82:85], v[30:33]
	v_mfma_f32_16x16x32_bf16 v[26:29], v[98:101], v[82:85], v[26:29]
	ds_read_b128 v[82:85], v104 offset:36864
	s_waitcnt lgkmcnt(0)
	v_mfma_f32_16x16x32_bf16 v[22:25], v[76:79], v[82:85], v[22:25]
	v_mfma_f32_16x16x32_bf16 v[18:21], v[90:93], v[82:85], v[18:21]
	v_mfma_f32_16x16x32_bf16 v[14:17], v[94:97], v[82:85], v[14:17]
	v_mfma_f32_16x16x32_bf16 v[10:13], v[98:101], v[82:85], v[10:13]
	ds_read_b128 v[82:85], v104 offset:38912
	s_waitcnt lgkmcnt(0)
	v_mfma_f32_16x16x32_bf16 v[6:9], v[76:79], v[82:85], v[6:9]
	ds_read_b128 v[76:79], v102 offset:49152
	v_mfma_f32_16x16x32_bf16 v[2:5], v[90:93], v[82:85], v[2:5]
	v_mfma_f32_16x16x32_bf16 v[90:93], v[94:97], v[82:85], v[58:61]
	v_mfma_f32_16x16x32_bf16 v[94:97], v[98:101], v[82:85], v[42:45]
	ds_read_b128 v[82:85], v102 offset:51200
	ds_read_b128 v[98:101], v102 offset:53248
	ds_read_b128 v[102:105], v102 offset:55296
	ds_read_b128 v[42:45], v81 offset:32768
	s_waitcnt lgkmcnt(0)
	v_mfma_f32_16x16x32_bf16 v[62:65], v[76:79], v[42:45], v[62:65]
	v_mfma_f32_16x16x32_bf16 v[58:61], v[82:85], v[42:45], v[54:57]
	v_mfma_f32_16x16x32_bf16 v[54:57], v[98:101], v[42:45], v[50:53]
	v_mfma_f32_16x16x32_bf16 v[50:53], v[102:105], v[42:45], v[46:49]
	v_mfma_f32_16x16x32_bf16 v[46:49], v[76:79], v[106:109], v[38:41]
	v_mfma_f32_16x16x32_bf16 v[42:45], v[82:85], v[106:109], v[34:37]
	v_mfma_f32_16x16x32_bf16 v[38:41], v[98:101], v[106:109], v[30:33]
	v_mfma_f32_16x16x32_bf16 v[34:37], v[102:105], v[106:109], v[26:29]
	ds_read_b128 v[106:109], v81 offset:36864
	v_and_b32_e32 v81, 64, v80
	v_add_u32_e32 v80, s11, v89
	s_waitcnt lgkmcnt(0)
	v_mfma_f32_16x16x32_bf16 v[30:33], v[76:79], v[106:109], v[22:25]
	s_barrier
	v_mfma_f32_16x16x32_bf16 v[26:29], v[82:85], v[106:109], v[18:21]
	v_mfma_f32_16x16x32_bf16 v[22:25], v[98:101], v[106:109], v[14:17]
	s_nop 2
	v_lshlrev_b32_e32 v14, 2, v74
	v_mfma_f32_16x16x32_bf16 v[18:21], v[102:105], v[106:109], v[10:13]
	v_or3_b32 v74, v14, v81, s4
	s_mov_b64 s[4:5], -1
	v_ashrrev_i32_e32 v81, 31, v80
	v_mfma_f32_16x16x32_bf16 v[10:13], v[82:85], v[110:113], v[2:5]
	v_ashrrev_i32_e32 v84, 8, v80
	v_ashrrev_i32_e32 v85, 31, v84
	s_nop 0
	v_and_b32_e32 v2, 0xcf, v80
	v_mfma_f32_16x16x32_bf16 v[14:17], v[76:79], v[110:113], v[6:9]
	v_lshlrev_b32_e32 v82, 1, v2
	v_add_u32_e32 v78, 0xfffff800, v74
	v_mfma_f32_16x16x32_bf16 v[6:9], v[98:101], v[110:113], v[90:93]
	v_mfma_f32_16x16x32_bf16 v[2:5], v[102:105], v[110:113], v[94:97]
	s_cbranch_vccz .LBB0_187
	v_lshlrev_b64 v[76:77], 13, v[80:81]
	v_lshl_add_u64 v[76:77], s[18:19], 0, v[76:77]
	v_mov_b32_e32 v79, v75
	v_lshl_add_u64 v[76:77], v[78:79], 2, v[76:77]
	global_store_dwordx4 v[76:77], v[62:65], off nt
	v_lshlrev_b64 v[76:77], 11, v[84:85]
	v_lshl_add_u64 v[76:77], v[76:77], 0, v[78:79]
	v_mad_u64_u32 v[90:91], s[4:5], v76, s60, v[162:163]
	v_mad_i32_i24 v91, v77, s60, v91
	v_mov_b32_e32 v83, v75
	v_lshl_add_u64 v[76:77], v[90:91], 0, v[82:83]
	v_cvt_pk_bf16_f32 v79, v62, s0
	global_store_short v[76:77], v79, off
	v_cvt_pk_bf16_f32 v79, v63, s0
	global_store_short v[76:77], v79, off offset:576
	v_cvt_pk_bf16_f32 v79, v64, s0
	global_store_short v[76:77], v79, off offset:1152
	v_cvt_pk_bf16_f32 v79, v65, s0
	global_store_short v[76:77], v79, off offset:1728
	s_mov_b64 s[4:5], 0

; #define GLDS_STAGE(st, kt_) do { \
;         _Pragma("unroll") for (int i_ = 0; i_ < FI; ++i_) { \
;             glds16(ap + (size_t)(32 * i_) * lda + (kt_) * 64, l3a + (st) + tid * 16 + i_ * 4096); \
;             glds16(bp + (size_t)(32 * i_) * ldb + (kt_) * 64, l3a + (st) + OPB + tid * 16 + i_ * 4096); } } while (0)
; #define GLDS_STAGE(st, kt_) do { \
;         _Pragma("unroll") for (int i_ = 0; i_ < 4; ++i_) { \
;             glds16(ap + (size_t)(64 * i_) * lda + (kt_) * 64, l3a + (st) + tid * 16 + i_ * 8192); \
;             glds16(bp + (size_t)(64 * i_) * ldb + (kt_) * 64, l3a + (st) + 32768 + tid * 16 + i_ * 8192); } } while (0)
; template <int WT, class Epi>
; DEV void gemm_tile(const bf16_t* __restrict__ A, int lda, const bf16_t* __restrict__ Bt, int ldb, int K, unsigned char* lds, const Epi& epi) {
;     ...
;     constexpr int NSTG = 65536 / STB;
; #pragma unroll
;     for (int s_ = 0; s_ < NSTG - 1; ++s_) if (s_ < nk) GLDS_STAGE(s_ * STB, s_);
;     const int aoff = (wr * WT + fr) * 128, boff = OPB + (wc * WT + fr) * 128, sw = fr & 7;
;     int cur = 0, nxt = (NSTG - 1) * STB;
;     for (int kt = 0; kt < nk; ++kt) {
;         if (NSTG == 4 && kt + 2 < nk) { if (FI == 2) asm volatile("s_waitcnt vmcnt(8)" ::: "memory"); else asm volatile("s_waitcnt vmcnt(0)" ::: "memory"); }
;         else asm volatile("s_waitcnt vmcnt(0)" ::: "memory");
;         __syncthreads();
;         if (kt + NSTG - 1 < nk) GLDS_STAGE(nxt, kt + NSTG - 1);
; #pragma unroll
;         for (int kh = 0; kh < 2; ++kh) {
;             bf16x8 af[FI], bfr[FI];
;             const int ch = ((kh * 4 + fq) ^ sw) << 4;
; #pragma unroll
;             for (int i = 0; i < FI; ++i) { af[i] = *(const bf16x8*)(lds + cur + aoff + i * 2048 + ch); bfr[i] = *(const bf16x8*)(lds + cur + boff + i * 2048 + ch); }
; #pragma unroll
;             for (int mi = 0; mi < FI; ++mi)
; #pragma unroll
;                 for (int ni = 0; ni < FI; ++ni) acc[mi][ni] = __builtin_amdgcn_mfma_f32_16x16x32_bf16(bfr[ni], af[mi], acc[mi][ni], 0, 0, 0);
;         }
;         nxt = cur; cur += STB; if (cur == NSTG * STB) cur = 0;
.Lg128s_1_loop:
	s_add_i32 s40, s53, s42
	s_xor_b32 s43, s42, 0x8000
	v_add_u32_e32 v122, s40, v84
	v_add_u32_e32 v123, s40, v89
	v_add_u32_e32 v143, v122, v82
	v_add_u32_e32 v144, v123, v82
	v_add_u32_e32 v122, v122, v85
	v_add_u32_e32 v123, v123, v85
	s_waitcnt vmcnt(0)
	s_barrier
	v_add_u32_e32 v142, s43, v83
	v_lshl_add_u64 v[124:125], v[78:79], 0, s[4:5]
	v_lshl_add_u64 v[126:127], v[76:77], 0, s[4:5]
	v_readfirstlane_b32 s38, v142
	s_add_i32 s39, s38, 0x4000
	ds_read_b128 v[90:93], v123 offset:16384
	ds_read_b128 v[94:97], v123 offset:18432
	ds_read_b128 v[106:109], v122
	ds_read_b128 v[110:113], v122 offset:2048
	ds_read_b128 v[98:101], v123 offset:20480
	ds_read_b128 v[102:105], v123 offset:22528
	ds_read_b128 v[114:117], v122 offset:4096
	ds_read_b128 v[118:121], v122 offset:6144
	s_waitcnt lgkmcnt(5)
	v_mfma_f32_16x16x32_bf16 v[62:65], v[90:93], v[106:109], v[62:65]
	v_mfma_f32_16x16x32_bf16 v[54:57], v[94:97], v[106:109], v[54:57]
	s_mov_b32 m0, s38
	s_nop 0
	global_load_lds_dwordx4 v[124:125], off
	s_waitcnt lgkmcnt(4)
	v_mfma_f32_16x16x32_bf16 v[38:41], v[90:93], v[110:113], v[38:41]
	v_mfma_f32_16x16x32_bf16 v[34:37], v[94:97], v[110:113], v[34:37]
	s_mov_b32 m0, s39
	s_nop 0
	global_load_lds_dwordx4 v[126:127], off
	s_waitcnt lgkmcnt(2)
	v_mfma_f32_16x16x32_bf16 v[50:53], v[98:101], v[106:109], v[50:53]
	v_mfma_f32_16x16x32_bf16 v[46:49], v[102:105], v[106:109], v[46:49]
	s_add_i32 s40, s38, 0x1000
	s_mov_b32 m0, s40
	v_lshl_add_u64 v[128:129], v[124:125], 0, s[30:31]
	global_load_lds_dwordx4 v[128:129], off
	v_mfma_f32_16x16x32_bf16 v[30:33], v[98:101], v[110:113], v[30:33]
	v_mfma_f32_16x16x32_bf16 v[26:29], v[102:105], v[110:113], v[26:29]
	s_add_i32 s40, s39, 0x1000
	s_mov_b32 m0, s40
	v_lshl_add_u64 v[140:141], v[126:127], 0, s[30:31]
	global_load_lds_dwordx4 v[140:141], off
	s_waitcnt lgkmcnt(1)
	v_mfma_f32_16x16x32_bf16 v[22:25], v[90:93], v[114:117], v[22:25]
	v_mfma_f32_16x16x32_bf16 v[18:21], v[94:97], v[114:117], v[18:21]
	s_add_i32 s40, s38, 0x2000
	s_mov_b32 m0, s40
	v_lshl_add_u64 v[128:129], v[124:125], 0, s[34:35]
	global_load_lds_dwordx4 v[128:129], off
	v_mfma_f32_16x16x32_bf16 v[14:17], v[98:101], v[114:117], v[14:17]
	v_mfma_f32_16x16x32_bf16 v[10:13], v[102:105], v[114:117], v[10:13]
	s_add_i32 s40, s39, 0x2000
	s_mov_b32 m0, s40
	v_lshl_add_u64 v[140:141], v[126:127], 0, s[34:35]
	global_load_lds_dwordx4 v[140:141], off
	s_waitcnt lgkmcnt(0)
	v_mfma_f32_16x16x32_bf16 v[6:9], v[90:93], v[118:121], v[6:9]
	v_mfma_f32_16x16x32_bf16 v[2:5], v[94:97], v[118:121], v[2:5]
	s_add_i32 s40, s38, 0x3000
	s_mov_b32 m0, s40
	v_lshl_add_u64 v[128:129], v[124:125], 0, s[36:37]
	global_load_lds_dwordx4 v[128:129], off
	v_mfma_f32_16x16x32_bf16 v[58:61], v[98:101], v[118:121], v[58:61]
	v_mfma_f32_16x16x32_bf16 v[42:45], v[102:105], v[118:121], v[42:45]
	s_add_i32 s40, s39, 0x3000
	s_mov_b32 m0, s40
	v_lshl_add_u64 v[140:141], v[126:127], 0, s[36:37]
	global_load_lds_dwordx4 v[140:141], off
	v_mov_b32_e32 v122, v143
	v_mov_b32_e32 v123, v144
	ds_read_b128 v[90:93], v123 offset:16384
	ds_read_b128 v[94:97], v123 offset:18432
	ds_read_b128 v[106:109], v122
	ds_read_b128 v[110:113], v122 offset:2048
	ds_read_b128 v[98:101], v123 offset:20480
	ds_read_b128 v[102:105], v123 offset:22528
	ds_read_b128 v[114:117], v122 offset:4096
	ds_read_b128 v[118:121], v122 offset:6144
	s_waitcnt lgkmcnt(5)
	v_mfma_f32_16x16x32_bf16 v[62:65], v[90:93], v[106:109], v[62:65]
	v_mfma_f32_16x16x32_bf16 v[54:57], v[94:97], v[106:109], v[54:57]
	s_waitcnt lgkmcnt(4)
	v_mfma_f32_16x16x32_bf16 v[38:41], v[90:93], v[110:113], v[38:41]
	v_mfma_f32_16x16x32_bf16 v[34:37], v[94:97], v[110:113], v[34:37]
	s_waitcnt lgkmcnt(2)
	v_mfma_f32_16x16x32_bf16 v[50:53], v[98:101], v[106:109], v[50:53]
	v_mfma_f32_16x16x32_bf16 v[46:49], v[102:105], v[106:109], v[46:49]
	v_mfma_f32_16x16x32_bf16 v[30:33], v[98:101], v[110:113], v[30:33]
	v_mfma_f32_16x16x32_bf16 v[26:29], v[102:105], v[110:113], v[26:29]
	s_waitcnt lgkmcnt(1)
	v_mfma_f32_16x16x32_bf16 v[22:25], v[90:93], v[114:117], v[22:25]
	v_mfma_f32_16x16x32_bf16 v[18:21], v[94:97], v[114:117], v[18:21]
	v_mfma_f32_16x16x32_bf16 v[14:17], v[98:101], v[114:117], v[14:17]
	v_mfma_f32_16x16x32_bf16 v[10:13], v[102:105], v[114:117], v[10:13]
	s_waitcnt lgkmcnt(0)
	v_mfma_f32_16x16x32_bf16 v[6:9], v[90:93], v[118:121], v[6:9]
	v_mfma_f32_16x16x32_bf16 v[2:5], v[94:97], v[118:121], v[2:5]
	v_mfma_f32_16x16x32_bf16 v[58:61], v[98:101], v[118:121], v[58:61]
	v_mfma_f32_16x16x32_bf16 v[42:45], v[102:105], v[118:121], v[42:45]
	s_add_u32 s4, s4, 0x80
	s_addc_u32 s5, s5, 0
	s_xor_b32 s42, s42, 0x8000
	s_cmp_lg_u32 s4, 0xf80
	s_cbranch_scc1 .Lg128s_1_loop
; template <int WT, class Epi>
; DEV void gemm_tile(const bf16_t* __restrict__ A, int lda, const bf16_t* __restrict__ Bt, int ldb, int K, unsigned char* lds, const Epi& epi) {
;     ...
;         for (int kh = 0; kh < 2; ++kh) {
;             bf16x8 af[FI], bfr[FI];
;             const int ch = ((kh * 4 + fq) ^ sw) << 4;
; #pragma unroll
;             for (int i = 0; i < FI; ++i) { af[i] = *(const bf16x8*)(lds + cur + aoff + i * 2048 + ch); bfr[i] = *(const bf16x8*)(lds + cur + boff + i * 2048 + ch); }
; #pragma unroll
;             for (int mi = 0; mi < FI; ++mi)
; #pragma unroll
;                 for (int ni = 0; ni < FI; ++ni) acc[mi][ni] = __builtin_amdgcn_mfma_f32_16x16x32_bf16(bfr[ni], af[mi], acc[mi][ni], 0, 0, 0);
;         }
;         nxt = cur; cur += STB; if (cur == NSTG * STB) cur = 0;
;     }
;     ...
;     __syncthreads();
;     if constexpr (Epi::STAGE) {
;         constexpr int RB = 4 * WT, CPR = RB / 16;
; #pragma unroll
;         for (int mi = 0; mi < FI; ++mi)
; #pragma unroll
;             for (int ni = 0; ni < FI; ++ni) {
;                 const int row = wr * WT + mi * 16 + fr, col = wc * WT + ni * 16 + fq * 4;
;                 const f32x4 v = epi.xform(row, col, acc[mi][ni]);
;                 uint2 w; w.x = cvt_pk_bf16(v[0], v[1]); w.y = cvt_pk_bf16(v[2], v[3]);
;                 *(uint2*)(lds + row * RB + ((((col >> 3) ^ (row & (CPR - 1))) << 4) | (((col >> 2) & 1) << 3))) = w;
;             }
;         __syncthreads();
; #pragma unroll
;         for (int i = 0; i < (2 * WT * CPR) / 256; ++i) {
;             const int idx = tid + 256 * i, row = idx / CPR, cp = idx % CPR, c = cp ^ (row & (CPR - 1));
;             const uint4 d = *(const uint4*)(lds + row * RB + (cp << 4));
;             *(uint4*)(epi.obase + (size_t)row * epi.old + c * 8) = epi.finish(row, c * 8, d);
;         }
;         __syncthreads();
;     } else {
; #pragma unroll
;         for (int mi = 0; mi < FI; ++mi)
; #pragma unroll
;             for (int ni = 0; ni < FI; ++ni) epi(wr * WT + mi * 16 + fr, wc * WT + ni * 16 + fq * 4, acc[mi][ni]);
;     DEV void operator()(int r, int c, f32x4 v) const {
;         const int row = m0 + r, col = n0 + c;
;         if (col < NPJ) {
;             store_bf4(proj + (size_t)row * NPJ + col, v);
;             const bool isconv = col < 3072, ispool = (col >= C_U && col < C_ZB);
;             if (isconv || ispool) {
;                 if (row < TP) {
	s_mov_b32 m0, s46
	v_add_u32_e32 v83, s53, v89
	v_add_u32_e32 v89, v83, v85
	s_waitcnt vmcnt(0)
	s_barrier
	ds_read_b128 v[76:79], v89 offset:49152
	ds_read_b128 v[94:97], v89 offset:51200
	ds_read_b128 v[98:101], v89 offset:53248
	ds_read_b128 v[102:105], v89 offset:55296
	v_add_u32_e32 v84, s53, v84
	v_add_u32_e32 v85, v84, v85
	ds_read_b128 v[90:93], v85 offset:32768
	v_add_u32_e32 v89, v84, v82
	ds_read_b128 v[110:113], v89 offset:36864
	s_waitcnt lgkmcnt(1)
	v_mfma_f32_16x16x32_bf16 v[62:65], v[76:79], v[90:93], v[62:65]
	ds_read_b128 v[114:117], v89 offset:38912
	s_lshl_b32 s4, s6, 7
	s_and_b32 s26, s10, 0x7ffffe0
	v_mfma_f32_16x16x32_bf16 v[54:57], v[94:97], v[90:93], v[54:57]
	s_cmpk_lg_i32 s26, 0x80
	s_cselect_b64 s[44:45], -1, 0
	v_mfma_f32_16x16x32_bf16 v[50:53], v[98:101], v[90:93], v[50:53]
	v_mfma_f32_16x16x32_bf16 v[46:49], v[102:105], v[90:93], v[46:49]
	ds_read_b128 v[90:93], v85 offset:34816
	s_waitcnt lgkmcnt(0)
	v_mfma_f32_16x16x32_bf16 v[38:41], v[76:79], v[90:93], v[38:41]
	v_mfma_f32_16x16x32_bf16 v[34:37], v[94:97], v[90:93], v[34:37]
	v_mfma_f32_16x16x32_bf16 v[30:33], v[98:101], v[90:93], v[30:33]
	v_mfma_f32_16x16x32_bf16 v[26:29], v[102:105], v[90:93], v[26:29]
	ds_read_b128 v[90:93], v85 offset:36864
	s_waitcnt lgkmcnt(0)
	v_mfma_f32_16x16x32_bf16 v[22:25], v[76:79], v[90:93], v[22:25]
	v_mfma_f32_16x16x32_bf16 v[18:21], v[94:97], v[90:93], v[18:21]
	v_mfma_f32_16x16x32_bf16 v[14:17], v[98:101], v[90:93], v[14:17]
	v_mfma_f32_16x16x32_bf16 v[10:13], v[102:105], v[90:93], v[10:13]
	ds_read_b128 v[90:93], v85 offset:38912
	s_waitcnt lgkmcnt(0)
	v_mfma_f32_16x16x32_bf16 v[6:9], v[76:79], v[90:93], v[6:9]
	v_add_u32_e32 v76, v83, v82
	ds_read_b128 v[82:85], v76 offset:51200
	ds_read_b128 v[106:109], v76 offset:55296
	v_mfma_f32_16x16x32_bf16 v[2:5], v[94:97], v[90:93], v[2:5]
	v_mfma_f32_16x16x32_bf16 v[94:97], v[98:101], v[90:93], v[58:61]
	ds_read_b128 v[98:101], v76 offset:49152
	v_mfma_f32_16x16x32_bf16 v[90:93], v[102:105], v[90:93], v[42:45]
	ds_read_b128 v[102:105], v76 offset:53248
	ds_read_b128 v[76:79], v89 offset:34816
	s_nop 0
	ds_read_b128 v[42:45], v89 offset:32768
	s_waitcnt lgkmcnt(0)
	v_mfma_f32_16x16x32_bf16 v[62:65], v[98:101], v[42:45], v[62:65]
	s_barrier
	v_mfma_f32_16x16x32_bf16 v[58:61], v[82:85], v[42:45], v[54:57]
	v_mfma_f32_16x16x32_bf16 v[54:57], v[102:105], v[42:45], v[50:53]
	v_mfma_f32_16x16x32_bf16 v[50:53], v[106:109], v[42:45], v[46:49]
	v_mfma_f32_16x16x32_bf16 v[46:49], v[98:101], v[76:79], v[38:41]
	v_mfma_f32_16x16x32_bf16 v[42:45], v[82:85], v[76:79], v[34:37]
	v_mfma_f32_16x16x32_bf16 v[38:41], v[102:105], v[76:79], v[30:33]
	v_mfma_f32_16x16x32_bf16 v[34:37], v[106:109], v[76:79], v[26:29]
	v_and_b32_e32 v76, 64, v80
	v_mfma_f32_16x16x32_bf16 v[26:29], v[82:85], v[110:113], v[18:21]
	s_nop 2
	v_lshlrev_b32_e32 v18, 2, v74
	v_add_u32_e32 v74, s68, v81
	v_or3_b32 v76, v18, v76, s4
	v_mfma_f32_16x16x32_bf16 v[30:33], v[98:101], v[110:113], v[22:25]
	v_ashrrev_i32_e32 v77, 31, v76
	v_cmp_lt_i32_e32 vcc, s62, v76
	s_and_b64 s[38:39], s[44:45], vcc
	v_mfma_f32_16x16x32_bf16 v[22:25], v[102:105], v[110:113], v[14:17]
	v_cmp_gt_i32_e64 s[12:13], s57, v74
	s_nor_b64 s[8:9], s[12:13], s[38:39]
	s_nop 0
	v_mad_i64_i32 v[14:15], s[4:5], v74, s58, v[172:173]
	v_lshl_add_u64 v[78:79], v[76:77], 1, v[14:15]
	v_mfma_f32_16x16x32_bf16 v[18:21], v[106:109], v[110:113], v[10:13]
	v_cmp_gt_i32_e64 s[4:5], s61, v76
	s_nop 1
	v_cvt_pk_bf16_f32 v10, v62, v63
	v_cvt_pk_bf16_f32 v11, v64, v65
	global_store_dwordx2 v[78:79], v[10:11], off
	v_mfma_f32_16x16x32_bf16 v[10:13], v[82:85], v[114:117], v[2:5]
	s_nop 2
	v_add_u32_e32 v2, 0xffffe000, v74
	v_mfma_f32_16x16x32_bf16 v[14:17], v[98:101], v[114:117], v[6:9]
	v_lshrrev_b32_e32 v82, 2, v2
	v_mfma_f32_16x16x32_bf16 v[6:9], v[102:105], v[114:117], v[94:97]
	v_mfma_f32_16x16x32_bf16 v[2:5], v[106:109], v[114:117], v[90:93]
	s_and_saveexec_b64 s[6:7], s[8:9]
	s_cbranch_execz .LBB0_234
	v_and_b32_e32 v74, 3, v80
	s_and_saveexec_b64 s[8:9], s[4:5]
	s_xor_b64 s[8:9], exec, s[8:9]
	s_cbranch_execz .LBB0_232
	v_cmp_ne_u32_e32 vcc, 0, v74
	s_and_saveexec_b64 s[10:11], vcc
	s_cbranch_execz .LBB0_231
	v_lshl_add_u32 v83, v82, 1, v82
	v_add3_u32 v74, v74, v83, -1
	v_mov_b64_e32 v[84:85], s[22:23]
	v_mad_u64_u32 v[84:85], s[40:41], v74, s58, v[84:85]
	v_lshl_add_u64 v[84:85], v[76:77], 2, v[84:85]
	global_store_dwordx4 v[84:85], v[62:65], off
